# remove redundant second accumulator zero-init before each GEMM K-loop (7 sites)
# speedup vs baseline: 1.0119x; 1.0119x over previous
; template <class Epi, class Sched, bool ALIGN_EPI = false, bool SP2 = false>
; __device__ __forceinline__ void gemm_phase(PG8_LAS unsigned char* lds, const Gemm g, const Sched& S, const Epi& E) {
;     ...
;         for (int t = 0; t < nt; t += 2) {
;             const bool last = (t == nt - 2);
;             const char* a1 = cA + (size_t)(t + 1) * kstep;
;             const char* a2 = last ? nA : cA + (size_t)(t + 2) * kstep; const char* b2 = last ? nB : cB + (size_t)(t + 2) * kstep;
;             const char* a3 = a2 + kstep; const char* b3 = b2 + kstep;
;     ...
; #pragma unroll
;         for (int a = 0; a < 2; ++a)
; #pragma unroll
;             for (int b = 0; b < 2; ++b)
; #pragma unroll
;                 for (int m = 0; m < 4; ++m)
; #pragma unroll
;                     for (int n = 0; n < 2; ++n) acc[a][b][m][n] = (f32x4){0.f, 0.f, 0.f, 0.f};
;         cur = nxt; cA = nA; cB = nB; ++ui;
.LBB0_214:
	v_mov_b32_e32 v2, v0
	v_mov_b32_e32 v3, v0
	v_mov_b32_e32 v1, v0
	v_mov_b64_e32 v[128:129], v[2:3]
	v_mov_b64_e32 v[124:125], v[2:3]
	v_mov_b64_e32 v[112:113], v[2:3]
	v_mov_b64_e32 v[108:109], v[2:3]
	v_mov_b64_e32 v[96:97], v[2:3]
	v_mov_b64_e32 v[92:93], v[2:3]
	v_mov_b64_e32 v[80:81], v[2:3]
	v_mov_b64_e32 v[76:77], v[2:3]
	v_mov_b64_e32 v[120:121], v[2:3]
	v_mov_b64_e32 v[116:117], v[2:3]
	v_mov_b64_e32 v[104:105], v[2:3]
	v_mov_b64_e32 v[100:101], v[2:3]
	v_mov_b64_e32 v[88:89], v[2:3]
	v_mov_b64_e32 v[84:85], v[2:3]
	v_mov_b64_e32 v[72:73], v[2:3]
	v_mov_b64_e32 v[68:69], v[2:3]
	v_mov_b64_e32 v[64:65], v[2:3]
	v_mov_b64_e32 v[60:61], v[2:3]
	v_mov_b64_e32 v[48:49], v[2:3]
	v_mov_b64_e32 v[44:45], v[2:3]
	v_mov_b64_e32 v[32:33], v[2:3]
	v_mov_b64_e32 v[28:29], v[2:3]
	v_mov_b64_e32 v[16:17], v[2:3]
	v_mov_b64_e32 v[12:13], v[2:3]
	v_mov_b64_e32 v[56:57], v[2:3]
	v_mov_b64_e32 v[52:53], v[2:3]
	v_mov_b64_e32 v[40:41], v[2:3]
	v_mov_b64_e32 v[36:37], v[2:3]
	v_mov_b64_e32 v[24:25], v[2:3]
	v_mov_b64_e32 v[20:21], v[2:3]
	v_mov_b64_e32 v[8:9], v[2:3]
	v_mov_b64_e32 v[126:127], v[0:1]
	v_mov_b64_e32 v[122:123], v[0:1]
	v_mov_b64_e32 v[110:111], v[0:1]
	v_mov_b64_e32 v[106:107], v[0:1]
	v_mov_b64_e32 v[94:95], v[0:1]
	v_mov_b64_e32 v[90:91], v[0:1]
	v_mov_b64_e32 v[78:79], v[0:1]
	v_mov_b64_e32 v[74:75], v[0:1]
	v_mov_b64_e32 v[118:119], v[0:1]
	v_mov_b64_e32 v[114:115], v[0:1]
	v_mov_b64_e32 v[102:103], v[0:1]
	v_mov_b64_e32 v[98:99], v[0:1]
	v_mov_b64_e32 v[86:87], v[0:1]
	v_mov_b64_e32 v[82:83], v[0:1]
	v_mov_b64_e32 v[70:71], v[0:1]
	v_mov_b64_e32 v[66:67], v[0:1]
	v_mov_b64_e32 v[62:63], v[0:1]
	v_mov_b64_e32 v[58:59], v[0:1]
	v_mov_b64_e32 v[46:47], v[0:1]
	v_mov_b64_e32 v[42:43], v[0:1]
	v_mov_b64_e32 v[30:31], v[0:1]
	v_mov_b64_e32 v[26:27], v[0:1]
	v_mov_b64_e32 v[14:15], v[0:1]
	v_mov_b64_e32 v[10:11], v[0:1]
	v_mov_b64_e32 v[54:55], v[0:1]
	v_mov_b64_e32 v[50:51], v[0:1]
	v_mov_b64_e32 v[38:39], v[0:1]
	v_mov_b64_e32 v[34:35], v[0:1]
	v_mov_b64_e32 v[22:23], v[0:1]
	v_mov_b64_e32 v[18:19], v[0:1]
	v_mov_b64_e32 v[6:7], v[0:1]
	v_mov_b64_e32 v[4:5], v[2:3]
	s_andn2_b64 vcc, exec, s[56:57]
	v_mov_b64_e32 v[2:3], v[0:1]
	s_cbranch_vccnz .LBB0_217
	s_add_u32 s0, s72, 0x80
	s_addc_u32 s1, s73, 0
	s_add_u32 s61, s6, 0x100
	s_addc_u32 s72, s7, 0
	s_mov_b32 s6, 0

; template <class Epi, class Sched, bool ALIGN_EPI = false, bool SP2 = false>
; __device__ __forceinline__ void gemm_phase(PG8_LAS unsigned char* lds, const Gemm g, const Sched& S, const Epi& E) {
;     ...
;         for (int t = 0; t < nt; t += 2) {
;             const bool last = (t == nt - 2);
;             const char* a1 = cA + (size_t)(t + 1) * kstep;
;             const char* a2 = last ? nA : cA + (size_t)(t + 2) * kstep; const char* b2 = last ? nB : cB + (size_t)(t + 2) * kstep;
;             const char* a3 = a2 + kstep; const char* b3 = b2 + kstep;
;     ...
; #pragma unroll
;         for (int a = 0; a < 2; ++a)
; #pragma unroll
;             for (int b = 0; b < 2; ++b)
; #pragma unroll
;                 for (int m = 0; m < 4; ++m)
; #pragma unroll
;                     for (int n = 0; n < 2; ++n) acc[a][b][m][n] = (f32x4){0.f, 0.f, 0.f, 0.f};
;         cur = nxt; cA = nA; cB = nB; ++ui;
.LBB0_458:
	v_mov_b32_e32 v123, 0
	s_andn2_b64 vcc, exec, s[42:43]
	v_mov_b32_e32 v122, v123
	v_mov_b32_e32 v121, v123
	v_mov_b32_e32 v120, v123
	v_mov_b32_e32 v127, v123
	v_mov_b32_e32 v126, v123
	v_mov_b32_e32 v125, v123
	v_mov_b32_e32 v124, v123
	v_mov_b32_e32 v111, v123
	v_mov_b32_e32 v110, v123
	v_mov_b32_e32 v109, v123
	v_mov_b32_e32 v108, v123
	v_mov_b32_e32 v107, v123
	v_mov_b32_e32 v106, v123
	v_mov_b32_e32 v105, v123
	v_mov_b32_e32 v104, v123
	v_mov_b32_e32 v95, v123
	v_mov_b32_e32 v94, v123
	v_mov_b32_e32 v93, v123
	v_mov_b32_e32 v92, v123
	v_mov_b32_e32 v91, v123
	v_mov_b32_e32 v90, v123
	v_mov_b32_e32 v89, v123
	v_mov_b32_e32 v88, v123
	v_mov_b32_e32 v79, v123
	v_mov_b32_e32 v78, v123
	v_mov_b32_e32 v77, v123
	v_mov_b32_e32 v76, v123
	v_mov_b32_e32 v75, v123
	v_mov_b32_e32 v74, v123
	v_mov_b32_e32 v73, v123
	v_mov_b32_e32 v72, v123
	v_mov_b32_e32 v119, v123
	v_mov_b32_e32 v118, v123
	v_mov_b32_e32 v117, v123
	v_mov_b32_e32 v116, v123
	v_mov_b32_e32 v115, v123
	v_mov_b32_e32 v114, v123
	v_mov_b32_e32 v113, v123
	v_mov_b32_e32 v112, v123
	v_mov_b32_e32 v103, v123
	v_mov_b32_e32 v102, v123
	v_mov_b32_e32 v101, v123
	v_mov_b32_e32 v100, v123
	v_mov_b32_e32 v99, v123
	v_mov_b32_e32 v98, v123
	v_mov_b32_e32 v97, v123
	v_mov_b32_e32 v96, v123
	v_mov_b32_e32 v87, v123
	v_mov_b32_e32 v86, v123
	v_mov_b32_e32 v85, v123
	v_mov_b32_e32 v84, v123
	v_mov_b32_e32 v83, v123
	v_mov_b32_e32 v82, v123
	v_mov_b32_e32 v81, v123
	v_mov_b32_e32 v80, v123
	v_mov_b32_e32 v71, v123
	v_mov_b32_e32 v70, v123
	v_mov_b32_e32 v69, v123
	v_mov_b32_e32 v68, v123
	v_mov_b32_e32 v67, v123
	v_mov_b32_e32 v66, v123
	v_mov_b32_e32 v65, v123
	v_mov_b32_e32 v64, v123
	v_mov_b32_e32 v63, v123
	v_mov_b32_e32 v62, v123
	v_mov_b32_e32 v61, v123
	v_mov_b32_e32 v60, v123
	v_mov_b32_e32 v59, v123
	v_mov_b32_e32 v58, v123
	v_mov_b32_e32 v57, v123
	v_mov_b32_e32 v56, v123
	v_mov_b32_e32 v47, v123
	v_mov_b32_e32 v46, v123
	v_mov_b32_e32 v45, v123
	v_mov_b32_e32 v44, v123
	v_mov_b32_e32 v43, v123
	v_mov_b32_e32 v42, v123
	v_mov_b32_e32 v41, v123
	v_mov_b32_e32 v40, v123
	v_mov_b32_e32 v31, v123
	v_mov_b32_e32 v30, v123
	v_mov_b32_e32 v29, v123
	v_mov_b32_e32 v28, v123
	v_mov_b32_e32 v27, v123
	v_mov_b32_e32 v26, v123
	v_mov_b32_e32 v25, v123
	v_mov_b32_e32 v24, v123
	v_mov_b32_e32 v15, v123
	v_mov_b32_e32 v14, v123
	v_mov_b32_e32 v13, v123
	v_mov_b32_e32 v12, v123
	v_mov_b32_e32 v11, v123
	v_mov_b32_e32 v10, v123
	v_mov_b32_e32 v9, v123
	v_mov_b32_e32 v8, v123
	v_mov_b32_e32 v55, v123
	v_mov_b32_e32 v54, v123
	v_mov_b32_e32 v53, v123
	v_mov_b32_e32 v52, v123
	v_mov_b32_e32 v51, v123
	v_mov_b32_e32 v50, v123
	v_mov_b32_e32 v49, v123
	v_mov_b32_e32 v48, v123
	v_mov_b32_e32 v39, v123
	v_mov_b32_e32 v38, v123
	v_mov_b32_e32 v37, v123
	v_mov_b32_e32 v36, v123
	v_mov_b32_e32 v35, v123
	v_mov_b32_e32 v34, v123
	v_mov_b32_e32 v33, v123
	v_mov_b32_e32 v32, v123
	v_mov_b32_e32 v23, v123
	v_mov_b32_e32 v22, v123
	v_mov_b32_e32 v21, v123
	v_mov_b32_e32 v20, v123
	v_mov_b32_e32 v19, v123
	v_mov_b32_e32 v18, v123
	v_mov_b32_e32 v17, v123
	v_mov_b32_e32 v16, v123
	v_mov_b32_e32 v7, v123
	v_mov_b32_e32 v6, v123
	v_mov_b32_e32 v5, v123
	v_mov_b32_e32 v4, v123
	v_mov_b32_e32 v3, v123
	v_mov_b32_e32 v2, v123
	v_mov_b32_e32 v1, v123
	v_mov_b32_e32 v0, v123
	s_cbranch_vccnz .LBB0_461
	s_add_u32 s0, s62, 0x80
	s_addc_u32 s1, s63, 0
	s_add_u32 s62, s60, 0x100
	s_addc_u32 s63, s61, 0
	s_mov_b32 s60, 0

; template <class Epi, class Sched, bool ALIGN_EPI = false, bool SP2 = false>
; __device__ __forceinline__ void gemm_phase(PG8_LAS unsigned char* lds, const Gemm g, const Sched& S, const Epi& E) {
;     ...
;         for (int t = 0; t < nt; t += 2) {
;             const bool last = (t == nt - 2);
;             const char* a1 = cA + (size_t)(t + 1) * kstep;
;             const char* a2 = last ? nA : cA + (size_t)(t + 2) * kstep; const char* b2 = last ? nB : cB + (size_t)(t + 2) * kstep;
;             const char* a3 = a2 + kstep; const char* b3 = b2 + kstep;
;     ...
; #pragma unroll
;         for (int a = 0; a < 2; ++a)
; #pragma unroll
;             for (int b = 0; b < 2; ++b)
; #pragma unroll
;                 for (int m = 0; m < 4; ++m)
; #pragma unroll
;                     for (int n = 0; n < 2; ++n) acc[a][b][m][n] = (f32x4){0.f, 0.f, 0.f, 0.f};
;         cur = nxt; cA = nA; cB = nB; ++ui;
.LBB0_533:
	v_mov_b32_e32 v123, 0
	s_andn2_b64 vcc, exec, s[44:45]
	v_mov_b32_e32 v122, v123
	v_mov_b32_e32 v121, v123
	v_mov_b32_e32 v120, v123
	v_mov_b32_e32 v127, v123
	v_mov_b32_e32 v126, v123
	v_mov_b32_e32 v125, v123
	v_mov_b32_e32 v124, v123
	v_mov_b32_e32 v111, v123
	v_mov_b32_e32 v110, v123
	v_mov_b32_e32 v109, v123
	v_mov_b32_e32 v108, v123
	v_mov_b32_e32 v107, v123
	v_mov_b32_e32 v106, v123
	v_mov_b32_e32 v105, v123
	v_mov_b32_e32 v104, v123
	v_mov_b32_e32 v95, v123
	v_mov_b32_e32 v94, v123
	v_mov_b32_e32 v93, v123
	v_mov_b32_e32 v92, v123
	v_mov_b32_e32 v91, v123
	v_mov_b32_e32 v90, v123
	v_mov_b32_e32 v89, v123
	v_mov_b32_e32 v88, v123
	v_mov_b32_e32 v79, v123
	v_mov_b32_e32 v78, v123
	v_mov_b32_e32 v77, v123
	v_mov_b32_e32 v76, v123
	v_mov_b32_e32 v75, v123
	v_mov_b32_e32 v74, v123
	v_mov_b32_e32 v73, v123
	v_mov_b32_e32 v72, v123
	v_mov_b32_e32 v119, v123
	v_mov_b32_e32 v118, v123
	v_mov_b32_e32 v117, v123
	v_mov_b32_e32 v116, v123
	v_mov_b32_e32 v115, v123
	v_mov_b32_e32 v114, v123
	v_mov_b32_e32 v113, v123
	v_mov_b32_e32 v112, v123
	v_mov_b32_e32 v103, v123
	v_mov_b32_e32 v102, v123
	v_mov_b32_e32 v101, v123
	v_mov_b32_e32 v100, v123
	v_mov_b32_e32 v99, v123
	v_mov_b32_e32 v98, v123
	v_mov_b32_e32 v97, v123
	v_mov_b32_e32 v96, v123
	v_mov_b32_e32 v87, v123
	v_mov_b32_e32 v86, v123
	v_mov_b32_e32 v85, v123
	v_mov_b32_e32 v84, v123
	v_mov_b32_e32 v83, v123
	v_mov_b32_e32 v82, v123
	v_mov_b32_e32 v81, v123
	v_mov_b32_e32 v80, v123
	v_mov_b32_e32 v71, v123
	v_mov_b32_e32 v70, v123
	v_mov_b32_e32 v69, v123
	v_mov_b32_e32 v68, v123
	v_mov_b32_e32 v67, v123
	v_mov_b32_e32 v66, v123
	v_mov_b32_e32 v65, v123
	v_mov_b32_e32 v64, v123
	v_mov_b32_e32 v63, v123
	v_mov_b32_e32 v62, v123
	v_mov_b32_e32 v61, v123
	v_mov_b32_e32 v60, v123
	v_mov_b32_e32 v59, v123
	v_mov_b32_e32 v58, v123
	v_mov_b32_e32 v57, v123
	v_mov_b32_e32 v56, v123
	v_mov_b32_e32 v47, v123
	v_mov_b32_e32 v46, v123
	v_mov_b32_e32 v45, v123
	v_mov_b32_e32 v44, v123
	v_mov_b32_e32 v43, v123
	v_mov_b32_e32 v42, v123
	v_mov_b32_e32 v41, v123
	v_mov_b32_e32 v40, v123
	v_mov_b32_e32 v31, v123
	v_mov_b32_e32 v30, v123
	v_mov_b32_e32 v29, v123
	v_mov_b32_e32 v28, v123
	v_mov_b32_e32 v27, v123
	v_mov_b32_e32 v26, v123
	v_mov_b32_e32 v25, v123
	v_mov_b32_e32 v24, v123
	v_mov_b32_e32 v15, v123
	v_mov_b32_e32 v14, v123
	v_mov_b32_e32 v13, v123
	v_mov_b32_e32 v12, v123
	v_mov_b32_e32 v11, v123
	v_mov_b32_e32 v10, v123
	v_mov_b32_e32 v9, v123
	v_mov_b32_e32 v8, v123
	v_mov_b32_e32 v55, v123
	v_mov_b32_e32 v54, v123
	v_mov_b32_e32 v53, v123
	v_mov_b32_e32 v52, v123
	v_mov_b32_e32 v51, v123
	v_mov_b32_e32 v50, v123
	v_mov_b32_e32 v49, v123
	v_mov_b32_e32 v48, v123
	v_mov_b32_e32 v39, v123
	v_mov_b32_e32 v38, v123
	v_mov_b32_e32 v37, v123
	v_mov_b32_e32 v36, v123
	v_mov_b32_e32 v35, v123
	v_mov_b32_e32 v34, v123
	v_mov_b32_e32 v33, v123
	v_mov_b32_e32 v32, v123
	v_mov_b32_e32 v23, v123
	v_mov_b32_e32 v22, v123
	v_mov_b32_e32 v21, v123
	v_mov_b32_e32 v20, v123
	v_mov_b32_e32 v19, v123
	v_mov_b32_e32 v18, v123
	v_mov_b32_e32 v17, v123
	v_mov_b32_e32 v16, v123
	v_mov_b32_e32 v7, v123
	v_mov_b32_e32 v6, v123
	v_mov_b32_e32 v5, v123
	v_mov_b32_e32 v4, v123
	v_mov_b32_e32 v3, v123
	v_mov_b32_e32 v2, v123
	v_mov_b32_e32 v1, v123
	v_mov_b32_e32 v0, v123
	s_cbranch_vccnz .LBB0_536
	s_add_u32 s58, s58, 0x80
	s_addc_u32 s59, s59, 0
	s_add_u32 s95, s60, 0x100
	s_addc_u32 s96, s61, 0
	s_mov_b32 s60, 0

; template <class Epi, class Sched, bool ALIGN_EPI = false, bool SP2 = false>
; __device__ __forceinline__ void gemm_phase(PG8_LAS unsigned char* lds, const Gemm g, const Sched& S, const Epi& E) {
;     ...
;         for (int t = 0; t < nt; t += 2) {
;             const bool last = (t == nt - 2);
;             const char* a1 = cA + (size_t)(t + 1) * kstep;
;             const char* a2 = last ? nA : cA + (size_t)(t + 2) * kstep; const char* b2 = last ? nB : cB + (size_t)(t + 2) * kstep;
;             const char* a3 = a2 + kstep; const char* b3 = b2 + kstep;
;     ...
; #pragma unroll
;         for (int a = 0; a < 2; ++a)
; #pragma unroll
;             for (int b = 0; b < 2; ++b)
; #pragma unroll
;                 for (int m = 0; m < 4; ++m)
; #pragma unroll
;                     for (int n = 0; n < 2; ++n) acc[a][b][m][n] = (f32x4){0.f, 0.f, 0.f, 0.f};
;         cur = nxt; cA = nA; cB = nB; ++ui;
.LBB0_726:
	v_mov_b32_e32 v123, 0
	s_andn2_b64 vcc, exec, s[46:47]
	v_mov_b32_e32 v122, v123
	v_mov_b32_e32 v121, v123
	v_mov_b32_e32 v120, v123
	v_mov_b32_e32 v127, v123
	v_mov_b32_e32 v126, v123
	v_mov_b32_e32 v125, v123
	v_mov_b32_e32 v124, v123
	v_mov_b32_e32 v111, v123
	v_mov_b32_e32 v110, v123
	v_mov_b32_e32 v109, v123
	v_mov_b32_e32 v108, v123
	v_mov_b32_e32 v107, v123
	v_mov_b32_e32 v106, v123
	v_mov_b32_e32 v105, v123
	v_mov_b32_e32 v104, v123
	v_mov_b32_e32 v95, v123
	v_mov_b32_e32 v94, v123
	v_mov_b32_e32 v93, v123
	v_mov_b32_e32 v92, v123
	v_mov_b32_e32 v91, v123
	v_mov_b32_e32 v90, v123
	v_mov_b32_e32 v89, v123
	v_mov_b32_e32 v88, v123
	v_mov_b32_e32 v79, v123
	v_mov_b32_e32 v78, v123
	v_mov_b32_e32 v77, v123
	v_mov_b32_e32 v76, v123
	v_mov_b32_e32 v75, v123
	v_mov_b32_e32 v74, v123
	v_mov_b32_e32 v73, v123
	v_mov_b32_e32 v72, v123
	v_mov_b32_e32 v119, v123
	v_mov_b32_e32 v118, v123
	v_mov_b32_e32 v117, v123
	v_mov_b32_e32 v116, v123
	v_mov_b32_e32 v115, v123
	v_mov_b32_e32 v114, v123
	v_mov_b32_e32 v113, v123
	v_mov_b32_e32 v112, v123
	v_mov_b32_e32 v103, v123
	v_mov_b32_e32 v102, v123
	v_mov_b32_e32 v101, v123
	v_mov_b32_e32 v100, v123
	v_mov_b32_e32 v99, v123
	v_mov_b32_e32 v98, v123
	v_mov_b32_e32 v97, v123
	v_mov_b32_e32 v96, v123
	v_mov_b32_e32 v87, v123
	v_mov_b32_e32 v86, v123
	v_mov_b32_e32 v85, v123
	v_mov_b32_e32 v84, v123
	v_mov_b32_e32 v83, v123
	v_mov_b32_e32 v82, v123
	v_mov_b32_e32 v81, v123
	v_mov_b32_e32 v80, v123
	v_mov_b32_e32 v71, v123
	v_mov_b32_e32 v70, v123
	v_mov_b32_e32 v69, v123
	v_mov_b32_e32 v68, v123
	v_mov_b32_e32 v67, v123
	v_mov_b32_e32 v66, v123
	v_mov_b32_e32 v65, v123
	v_mov_b32_e32 v64, v123
	v_mov_b32_e32 v63, v123
	v_mov_b32_e32 v62, v123
	v_mov_b32_e32 v61, v123
	v_mov_b32_e32 v60, v123
	v_mov_b32_e32 v59, v123
	v_mov_b32_e32 v58, v123
	v_mov_b32_e32 v57, v123
	v_mov_b32_e32 v56, v123
	v_mov_b32_e32 v47, v123
	v_mov_b32_e32 v46, v123
	v_mov_b32_e32 v45, v123
	v_mov_b32_e32 v44, v123
	v_mov_b32_e32 v43, v123
	v_mov_b32_e32 v42, v123
	v_mov_b32_e32 v41, v123
	v_mov_b32_e32 v40, v123
	v_mov_b32_e32 v31, v123
	v_mov_b32_e32 v30, v123
	v_mov_b32_e32 v29, v123
	v_mov_b32_e32 v28, v123
	v_mov_b32_e32 v27, v123
	v_mov_b32_e32 v26, v123
	v_mov_b32_e32 v25, v123
	v_mov_b32_e32 v24, v123
	v_mov_b32_e32 v15, v123
	v_mov_b32_e32 v14, v123
	v_mov_b32_e32 v13, v123
	v_mov_b32_e32 v12, v123
	v_mov_b32_e32 v11, v123
	v_mov_b32_e32 v10, v123
	v_mov_b32_e32 v9, v123
	v_mov_b32_e32 v8, v123
	v_mov_b32_e32 v55, v123
	v_mov_b32_e32 v54, v123
	v_mov_b32_e32 v53, v123
	v_mov_b32_e32 v52, v123
	v_mov_b32_e32 v51, v123
	v_mov_b32_e32 v50, v123
	v_mov_b32_e32 v49, v123
	v_mov_b32_e32 v48, v123
	v_mov_b32_e32 v39, v123
	v_mov_b32_e32 v38, v123
	v_mov_b32_e32 v37, v123
	v_mov_b32_e32 v36, v123
	v_mov_b32_e32 v35, v123
	v_mov_b32_e32 v34, v123
	v_mov_b32_e32 v33, v123
	v_mov_b32_e32 v32, v123
	v_mov_b32_e32 v23, v123
	v_mov_b32_e32 v22, v123
	v_mov_b32_e32 v21, v123
	v_mov_b32_e32 v20, v123
	v_mov_b32_e32 v19, v123
	v_mov_b32_e32 v18, v123
	v_mov_b32_e32 v17, v123
	v_mov_b32_e32 v16, v123
	v_mov_b32_e32 v7, v123
	v_mov_b32_e32 v6, v123
	v_mov_b32_e32 v5, v123
	v_mov_b32_e32 v4, v123
	v_mov_b32_e32 v3, v123
	v_mov_b32_e32 v2, v123
	v_mov_b32_e32 v1, v123
	v_mov_b32_e32 v0, v123
	s_cbranch_vccnz .LBB0_729
	s_add_u32 s6, s6, 0x80
	s_addc_u32 s7, s7, 0
	s_add_u32 s79, s52, 0x100
	s_addc_u32 s80, s53, 0
	s_mov_b32 s52, 0

; template <class Epi, class Sched, bool ALIGN_EPI = false, bool SP2 = false>
; __device__ __forceinline__ void gemm_phase(PG8_LAS unsigned char* lds, const Gemm g, const Sched& S, const Epi& E) {
;     ...
;         for (int t = 0; t < nt; t += 2) {
;             const bool last = (t == nt - 2);
;             const char* a1 = cA + (size_t)(t + 1) * kstep;
;             const char* a2 = last ? nA : cA + (size_t)(t + 2) * kstep; const char* b2 = last ? nB : cB + (size_t)(t + 2) * kstep;
;             const char* a3 = a2 + kstep; const char* b3 = b2 + kstep;
;     ...
; #pragma unroll
;         for (int a = 0; a < 2; ++a)
; #pragma unroll
;             for (int b = 0; b < 2; ++b)
; #pragma unroll
;                 for (int m = 0; m < 4; ++m)
; #pragma unroll
;                     for (int n = 0; n < 2; ++n) acc[a][b][m][n] = (f32x4){0.f, 0.f, 0.f, 0.f};
;         cur = nxt; cA = nA; cB = nB; ++ui;
.LBB0_873:
	v_mov_b32_e32 v127, 0
	s_andn2_b64 vcc, exec, s[44:45]
	v_mov_b32_e32 v126, v127
	v_mov_b32_e32 v125, v127
	v_mov_b32_e32 v124, v127
	v_mov_b32_e32 v123, v127
	v_mov_b32_e32 v122, v127
	v_mov_b32_e32 v121, v127
	v_mov_b32_e32 v120, v127
	v_mov_b32_e32 v111, v127
	v_mov_b32_e32 v110, v127
	v_mov_b32_e32 v109, v127
	v_mov_b32_e32 v108, v127
	v_mov_b32_e32 v107, v127
	v_mov_b32_e32 v106, v127
	v_mov_b32_e32 v105, v127
	v_mov_b32_e32 v104, v127
	v_mov_b32_e32 v95, v127
	v_mov_b32_e32 v94, v127
	v_mov_b32_e32 v93, v127
	v_mov_b32_e32 v92, v127
	v_mov_b32_e32 v91, v127
	v_mov_b32_e32 v90, v127
	v_mov_b32_e32 v89, v127
	v_mov_b32_e32 v88, v127
	v_mov_b32_e32 v79, v127
	v_mov_b32_e32 v78, v127
	v_mov_b32_e32 v77, v127
	v_mov_b32_e32 v76, v127
	v_mov_b32_e32 v75, v127
	v_mov_b32_e32 v74, v127
	v_mov_b32_e32 v73, v127
	v_mov_b32_e32 v72, v127
	v_mov_b32_e32 v119, v127
	v_mov_b32_e32 v118, v127
	v_mov_b32_e32 v117, v127
	v_mov_b32_e32 v116, v127
	v_mov_b32_e32 v115, v127
	v_mov_b32_e32 v114, v127
	v_mov_b32_e32 v113, v127
	v_mov_b32_e32 v112, v127
	v_mov_b32_e32 v103, v127
	v_mov_b32_e32 v102, v127
	v_mov_b32_e32 v101, v127
	v_mov_b32_e32 v100, v127
	v_mov_b32_e32 v99, v127
	v_mov_b32_e32 v98, v127
	v_mov_b32_e32 v97, v127
	v_mov_b32_e32 v96, v127
	v_mov_b32_e32 v87, v127
	v_mov_b32_e32 v86, v127
	v_mov_b32_e32 v85, v127
	v_mov_b32_e32 v84, v127
	v_mov_b32_e32 v83, v127
	v_mov_b32_e32 v82, v127
	v_mov_b32_e32 v81, v127
	v_mov_b32_e32 v80, v127
	v_mov_b32_e32 v71, v127
	v_mov_b32_e32 v70, v127
	v_mov_b32_e32 v69, v127
	v_mov_b32_e32 v68, v127
	v_mov_b32_e32 v67, v127
	v_mov_b32_e32 v66, v127
	v_mov_b32_e32 v65, v127
	v_mov_b32_e32 v64, v127
	v_mov_b32_e32 v63, v127
	v_mov_b32_e32 v62, v127
	v_mov_b32_e32 v61, v127
	v_mov_b32_e32 v60, v127
	v_mov_b32_e32 v59, v127
	v_mov_b32_e32 v58, v127
	v_mov_b32_e32 v57, v127
	v_mov_b32_e32 v56, v127
	v_mov_b32_e32 v47, v127
	v_mov_b32_e32 v46, v127
	v_mov_b32_e32 v45, v127
	v_mov_b32_e32 v44, v127
	v_mov_b32_e32 v43, v127
	v_mov_b32_e32 v42, v127
	v_mov_b32_e32 v41, v127
	v_mov_b32_e32 v40, v127
	v_mov_b32_e32 v31, v127
	v_mov_b32_e32 v30, v127
	v_mov_b32_e32 v29, v127
	v_mov_b32_e32 v28, v127
	v_mov_b32_e32 v27, v127
	v_mov_b32_e32 v26, v127
	v_mov_b32_e32 v25, v127
	v_mov_b32_e32 v24, v127
	v_mov_b32_e32 v15, v127
	v_mov_b32_e32 v14, v127
	v_mov_b32_e32 v13, v127
	v_mov_b32_e32 v12, v127
	v_mov_b32_e32 v11, v127
	v_mov_b32_e32 v10, v127
	v_mov_b32_e32 v9, v127
	v_mov_b32_e32 v8, v127
	v_mov_b32_e32 v55, v127
	v_mov_b32_e32 v54, v127
	v_mov_b32_e32 v53, v127
	v_mov_b32_e32 v52, v127
	v_mov_b32_e32 v51, v127
	v_mov_b32_e32 v50, v127
	v_mov_b32_e32 v49, v127
	v_mov_b32_e32 v48, v127
	v_mov_b32_e32 v39, v127
	v_mov_b32_e32 v38, v127
	v_mov_b32_e32 v37, v127
	v_mov_b32_e32 v36, v127
	v_mov_b32_e32 v35, v127
	v_mov_b32_e32 v34, v127
	v_mov_b32_e32 v33, v127
	v_mov_b32_e32 v32, v127
	v_mov_b32_e32 v23, v127
	v_mov_b32_e32 v22, v127
	v_mov_b32_e32 v21, v127
	v_mov_b32_e32 v20, v127
	v_mov_b32_e32 v19, v127
	v_mov_b32_e32 v18, v127
	v_mov_b32_e32 v17, v127
	v_mov_b32_e32 v16, v127
	v_mov_b32_e32 v7, v127
	v_mov_b32_e32 v6, v127
	s_waitcnt lgkmcnt(0)
	v_mov_b32_e32 v5, v127
	v_mov_b32_e32 v4, v127
	v_mov_b32_e32 v3, v127
	v_mov_b32_e32 v2, v127
	v_mov_b32_e32 v1, v127
	v_mov_b32_e32 v0, v127
	s_cbranch_vccnz .LBB0_876
	s_add_u32 s50, s50, 0x80
	s_addc_u32 s51, s51, 0
	s_add_u32 s78, s52, 0x100
	s_addc_u32 s79, s53, 0
	s_mov_b32 s52, 0

; template <class Epi, class Sched, bool ALIGN_EPI = false, bool SP2 = false>
; __device__ __forceinline__ void gemm_phase(PG8_LAS unsigned char* lds, const Gemm g, const Sched& S, const Epi& E) {
;     ...
;         for (int t = 0; t < nt; t += 2) {
;             const bool last = (t == nt - 2);
;             const char* a1 = cA + (size_t)(t + 1) * kstep;
;             const char* a2 = last ? nA : cA + (size_t)(t + 2) * kstep; const char* b2 = last ? nB : cB + (size_t)(t + 2) * kstep;
;             const char* a3 = a2 + kstep; const char* b3 = b2 + kstep;
;     ...
; #pragma unroll
;         for (int a = 0; a < 2; ++a)
; #pragma unroll
;             for (int b = 0; b < 2; ++b)
; #pragma unroll
;                 for (int m = 0; m < 4; ++m)
; #pragma unroll
;                     for (int n = 0; n < 2; ++n) acc[a][b][m][n] = (f32x4){0.f, 0.f, 0.f, 0.f};
;         cur = nxt; cA = nA; cB = nB; ++ui;
.LBB0_1019:
	v_mov_b32_e32 v127, 0
	s_and_b64 vcc, exec, s[4:5]
	v_mov_b32_e32 v126, v127
	v_mov_b32_e32 v125, v127
	v_mov_b32_e32 v124, v127
	v_mov_b32_e32 v119, v127
	v_mov_b32_e32 v118, v127
	v_mov_b32_e32 v117, v127
	v_mov_b32_e32 v116, v127
	v_mov_b32_e32 v111, v127
	v_mov_b32_e32 v110, v127
	v_mov_b32_e32 v109, v127
	v_mov_b32_e32 v108, v127
	v_mov_b32_e32 v103, v127
	v_mov_b32_e32 v102, v127
	v_mov_b32_e32 v101, v127
	v_mov_b32_e32 v100, v127
	v_mov_b32_e32 v95, v127
	v_mov_b32_e32 v94, v127
	v_mov_b32_e32 v93, v127
	v_mov_b32_e32 v92, v127
	v_mov_b32_e32 v87, v127
	v_mov_b32_e32 v86, v127
	v_mov_b32_e32 v85, v127
	v_mov_b32_e32 v84, v127
	v_mov_b32_e32 v79, v127
	v_mov_b32_e32 v78, v127
	v_mov_b32_e32 v77, v127
	v_mov_b32_e32 v76, v127
	v_mov_b32_e32 v71, v127
	v_mov_b32_e32 v70, v127
	v_mov_b32_e32 v69, v127
	v_mov_b32_e32 v68, v127
	v_mov_b32_e32 v123, v127
	v_mov_b32_e32 v122, v127
	v_mov_b32_e32 v121, v127
	v_mov_b32_e32 v120, v127
	v_mov_b32_e32 v115, v127
	v_mov_b32_e32 v114, v127
	v_mov_b32_e32 v113, v127
	v_mov_b32_e32 v112, v127
	v_mov_b32_e32 v107, v127
	v_mov_b32_e32 v106, v127
	v_mov_b32_e32 v105, v127
	v_mov_b32_e32 v104, v127
	v_mov_b32_e32 v99, v127
	v_mov_b32_e32 v98, v127
	v_mov_b32_e32 v97, v127
	v_mov_b32_e32 v96, v127
	v_mov_b32_e32 v91, v127
	v_mov_b32_e32 v90, v127
	v_mov_b32_e32 v89, v127
	v_mov_b32_e32 v88, v127
	v_mov_b32_e32 v83, v127
	v_mov_b32_e32 v82, v127
	v_mov_b32_e32 v81, v127
	v_mov_b32_e32 v80, v127
	v_mov_b32_e32 v75, v127
	v_mov_b32_e32 v74, v127
	v_mov_b32_e32 v73, v127
	v_mov_b32_e32 v72, v127
	v_mov_b32_e32 v67, v127
	v_mov_b32_e32 v66, v127
	v_mov_b32_e32 v65, v127
	v_mov_b32_e32 v64, v127
	v_mov_b32_e32 v63, v127
	v_mov_b32_e32 v62, v127
	v_mov_b32_e32 v61, v127
	v_mov_b32_e32 v60, v127
	v_mov_b32_e32 v55, v127
	v_mov_b32_e32 v54, v127
	v_mov_b32_e32 v53, v127
	v_mov_b32_e32 v52, v127
	v_mov_b32_e32 v47, v127
	v_mov_b32_e32 v46, v127
	v_mov_b32_e32 v45, v127
	v_mov_b32_e32 v44, v127
	v_mov_b32_e32 v39, v127
	v_mov_b32_e32 v38, v127
	v_mov_b32_e32 v37, v127
	v_mov_b32_e32 v36, v127
	v_mov_b32_e32 v31, v127
	v_mov_b32_e32 v30, v127
	v_mov_b32_e32 v29, v127
	v_mov_b32_e32 v28, v127
	v_mov_b32_e32 v23, v127
	v_mov_b32_e32 v22, v127
	v_mov_b32_e32 v21, v127
	v_mov_b32_e32 v20, v127
	v_mov_b32_e32 v15, v127
	v_mov_b32_e32 v14, v127
	v_mov_b32_e32 v13, v127
	v_mov_b32_e32 v12, v127
	v_mov_b32_e32 v7, v127
	v_mov_b32_e32 v6, v127
	v_mov_b32_e32 v5, v127
	v_mov_b32_e32 v4, v127
	v_mov_b32_e32 v59, v127
	v_mov_b32_e32 v58, v127
	v_mov_b32_e32 v57, v127
	v_mov_b32_e32 v56, v127
	v_mov_b32_e32 v51, v127
	v_mov_b32_e32 v50, v127
	v_mov_b32_e32 v49, v127
	v_mov_b32_e32 v48, v127
	v_mov_b32_e32 v43, v127
	v_mov_b32_e32 v42, v127
	v_mov_b32_e32 v41, v127
	v_mov_b32_e32 v40, v127
	v_mov_b32_e32 v35, v127
	v_mov_b32_e32 v34, v127
	v_mov_b32_e32 v33, v127
	v_mov_b32_e32 v32, v127
	v_mov_b32_e32 v27, v127
	v_mov_b32_e32 v26, v127
	v_mov_b32_e32 v25, v127
	v_mov_b32_e32 v24, v127
	v_mov_b32_e32 v19, v127
	v_mov_b32_e32 v18, v127
	v_mov_b32_e32 v17, v127
	v_mov_b32_e32 v16, v127
	v_mov_b32_e32 v11, v127
	v_mov_b32_e32 v10, v127
	v_mov_b32_e32 v9, v127
	v_mov_b32_e32 v8, v127
	v_mov_b32_e32 v3, v127
	v_mov_b32_e32 v2, v127
	v_mov_b32_e32 v1, v127
	v_mov_b32_e32 v0, v127
	s_cbranch_vccnz .LBB0_1022
	s_add_u32 s42, s42, 0x80
	s_addc_u32 s43, s43, 0
	s_add_u32 s68, s44, 0x100
	s_addc_u32 s69, s45, 0
	s_mov_b32 s44, 0

; template <class Epi, class Sched, bool ALIGN_EPI = false, bool SP2 = false>
; __device__ __forceinline__ void gemm_phase(PG8_LAS unsigned char* lds, const Gemm g, const Sched& S, const Epi& E) {
;     ...
;         for (int t = 0; t < nt; t += 2) {
;             const bool last = (t == nt - 2);
;             const char* a1 = cA + (size_t)(t + 1) * kstep;
;             const char* a2 = last ? nA : cA + (size_t)(t + 2) * kstep; const char* b2 = last ? nB : cB + (size_t)(t + 2) * kstep;
;             const char* a3 = a2 + kstep; const char* b3 = b2 + kstep;
;     ...
; #pragma unroll
;         for (int a = 0; a < 2; ++a)
; #pragma unroll
;             for (int b = 0; b < 2; ++b)
; #pragma unroll
;                 for (int m = 0; m < 4; ++m)
; #pragma unroll
;                     for (int n = 0; n < 2; ++n) acc[a][b][m][n] = (f32x4){0.f, 0.f, 0.f, 0.f};
;         cur = nxt; cA = nA; cB = nB; ++ui;
.LBB0_1102:
	v_mov_b32_e32 v127, 0
	s_andn2_b64 vcc, exec, s[38:39]
	v_mov_b32_e32 v126, v127
	v_mov_b32_e32 v125, v127
	v_mov_b32_e32 v124, v127
	v_mov_b32_e32 v123, v127
	v_mov_b32_e32 v122, v127
	v_mov_b32_e32 v121, v127
	v_mov_b32_e32 v120, v127
	v_mov_b32_e32 v111, v127
	v_mov_b32_e32 v110, v127
	v_mov_b32_e32 v109, v127
	v_mov_b32_e32 v108, v127
	v_mov_b32_e32 v107, v127
	v_mov_b32_e32 v106, v127
	v_mov_b32_e32 v105, v127
	v_mov_b32_e32 v104, v127
	v_mov_b32_e32 v95, v127
	v_mov_b32_e32 v94, v127
	v_mov_b32_e32 v93, v127
	v_mov_b32_e32 v92, v127
	v_mov_b32_e32 v91, v127
	v_mov_b32_e32 v90, v127
	v_mov_b32_e32 v89, v127
	v_mov_b32_e32 v88, v127
	v_mov_b32_e32 v79, v127
	v_mov_b32_e32 v78, v127
	v_mov_b32_e32 v77, v127
	v_mov_b32_e32 v76, v127
	v_mov_b32_e32 v75, v127
	v_mov_b32_e32 v74, v127
	v_mov_b32_e32 v73, v127
	v_mov_b32_e32 v72, v127
	v_mov_b32_e32 v119, v127
	v_mov_b32_e32 v118, v127
	v_mov_b32_e32 v117, v127
	v_mov_b32_e32 v116, v127
	v_mov_b32_e32 v115, v127
	v_mov_b32_e32 v114, v127
	v_mov_b32_e32 v113, v127
	v_mov_b32_e32 v112, v127
	v_mov_b32_e32 v103, v127
	v_mov_b32_e32 v102, v127
	v_mov_b32_e32 v101, v127
	v_mov_b32_e32 v100, v127
	v_mov_b32_e32 v99, v127
	v_mov_b32_e32 v98, v127
	v_mov_b32_e32 v97, v127
	v_mov_b32_e32 v96, v127
	v_mov_b32_e32 v87, v127
	v_mov_b32_e32 v86, v127
	v_mov_b32_e32 v85, v127
	v_mov_b32_e32 v84, v127
	v_mov_b32_e32 v83, v127
	v_mov_b32_e32 v82, v127
	v_mov_b32_e32 v81, v127
	v_mov_b32_e32 v80, v127
	v_mov_b32_e32 v71, v127
	v_mov_b32_e32 v70, v127
	v_mov_b32_e32 v69, v127
	v_mov_b32_e32 v68, v127
	v_mov_b32_e32 v67, v127
	v_mov_b32_e32 v66, v127
	v_mov_b32_e32 v65, v127
	v_mov_b32_e32 v64, v127
	v_mov_b32_e32 v63, v127
	v_mov_b32_e32 v62, v127
	v_mov_b32_e32 v61, v127
	v_mov_b32_e32 v60, v127
	v_mov_b32_e32 v59, v127
	v_mov_b32_e32 v58, v127
	v_mov_b32_e32 v57, v127
	v_mov_b32_e32 v56, v127
	v_mov_b32_e32 v47, v127
	v_mov_b32_e32 v46, v127
	v_mov_b32_e32 v45, v127
	v_mov_b32_e32 v44, v127
	v_mov_b32_e32 v43, v127
	v_mov_b32_e32 v42, v127
	v_mov_b32_e32 v41, v127
	v_mov_b32_e32 v40, v127
	v_mov_b32_e32 v31, v127
	v_mov_b32_e32 v30, v127
	v_mov_b32_e32 v29, v127
	v_mov_b32_e32 v28, v127
	v_mov_b32_e32 v27, v127
	v_mov_b32_e32 v26, v127
	v_mov_b32_e32 v25, v127
	v_mov_b32_e32 v24, v127
	v_mov_b32_e32 v15, v127
	v_mov_b32_e32 v14, v127
	v_mov_b32_e32 v13, v127
	v_mov_b32_e32 v12, v127
	v_mov_b32_e32 v11, v127
	v_mov_b32_e32 v10, v127
	v_mov_b32_e32 v9, v127
	v_mov_b32_e32 v8, v127
	v_mov_b32_e32 v55, v127
	v_mov_b32_e32 v54, v127
	v_mov_b32_e32 v53, v127
	v_mov_b32_e32 v52, v127
	v_mov_b32_e32 v51, v127
	v_mov_b32_e32 v50, v127
	v_mov_b32_e32 v49, v127
	v_mov_b32_e32 v48, v127
	v_mov_b32_e32 v39, v127
	v_mov_b32_e32 v38, v127
	v_mov_b32_e32 v37, v127
	v_mov_b32_e32 v36, v127
	v_mov_b32_e32 v35, v127
	v_mov_b32_e32 v34, v127
	v_mov_b32_e32 v33, v127
	v_mov_b32_e32 v32, v127
	v_mov_b32_e32 v23, v127
	v_mov_b32_e32 v22, v127
	v_mov_b32_e32 v21, v127
	v_mov_b32_e32 v20, v127
	v_mov_b32_e32 v19, v127
	v_mov_b32_e32 v18, v127
	v_mov_b32_e32 v17, v127
	v_mov_b32_e32 v16, v127
	v_mov_b32_e32 v7, v127
	v_mov_b32_e32 v6, v127
	s_waitcnt lgkmcnt(0)
	v_mov_b32_e32 v5, v127
	v_mov_b32_e32 v4, v127
	v_mov_b32_e32 v3, v127
	v_mov_b32_e32 v2, v127
	v_mov_b32_e32 v1, v127
	v_mov_b32_e32 v0, v127
	s_cbranch_vccnz .LBB0_1105
	s_add_u32 s44, s44, 0x80
	s_addc_u32 s45, s45, 0
	s_add_u32 s68, s46, 0x100
	s_addc_u32 s69, s47, 0
	s_mov_b32 s46, 0
